# f32 GEMM epilogues (out-proj, cross out-proj, FFN-out): v_permlane32_swap between the two dwordx4 pieces of each lane so every store writes 64 contiguous bytes per row instead of interleaved 16-byte p
# speedup vs baseline: 1.0197x; 1.0025x over previous
; DI void hg_out_units(LAS unsigned char* L, int u0, int G, const float* LOGF, const bf16* QHG, const bf16* IHG, const bf16* GHG, const bf16* ST, const float* og, bf16* MIX, int tid, int wave, int lane) {
;     ...
;     const int c = tid & 127, seg = tid >> 7;
;     const int lr = lane & 15, quad = lane >> 4, tt = wave >> 1, dh = wave & 1;
;     int unit = u0; if (unit >= 2048) return;
;     float g[16]; bf16 qraw[16]; bf16x8 v8[2];
;     ...
;     HGO_LOAD(unit);
.LBB0_332:
	s_or_b64 exec, exec, s[0:1]
	s_mov_b32 s0, -1
	s_waitcnt lgkmcnt(0)
	s_barrier
	s_mov_b64 s[24:25], 0
	v_mbcnt_lo_u32_b32 v0, s0, 0
	v_mbcnt_hi_u32_b32 v0, s0, v0
	v_add_u32_e32 v8, s68, v0
	s_and_b64 vcc, exec, s[4:5]
	v_readfirstlane_b32 s0, v8
	s_cbranch_vccnz .LBB0_352
	v_readlane_b32 s4, v252, 0
	v_mov_b64_e32 v[0:1], s[24:25]
	v_readlane_b32 s5, v252, 1
	v_readlane_b32 s6, v252, 2
	v_readlane_b32 s7, v252, 3
	s_mov_b64 s[4:5], 0x1b000000
	s_lshl_b32 s36, s46, 7
	v_lshl_add_u64 v[84:85], s[6:7], 0, v[0:1]
	v_lshl_add_u64 v[86:87], v[84:85], 0, s[4:5]
	s_mov_b64 s[4:5], 0x11000000
	v_lshl_add_u64 v[88:89], v[84:85], 0, s[4:5]
	s_mov_b64 s[4:5], 0x19000000
	v_readlane_b32 s8, v252, 39
	v_lshl_add_u64 v[90:91], v[84:85], 0, s[4:5]
	s_lshl_b64 s[4:5], s[36:37], 2
	v_readlane_b32 s10, v252, 41
	v_readlane_b32 s11, v252, 42
	s_add_u32 s68, s10, s4
	s_addc_u32 s69, s11, s5
	s_mov_b64 s[4:5], 0x17000000
	v_ashrrev_i32_e32 v23, 7, v8
	v_lshl_add_u64 v[10:11], v[84:85], 0, s[4:5]
	v_lshlrev_b32_e32 v92, 4, v23
	v_readlane_b32 s4, v253, 21
	v_ashrrev_i32_e32 v93, 31, v92
	v_readlane_b32 s5, v253, 22
	s_waitcnt vmcnt(3)
	v_and_b32_e32 v128, 0x7f, v8
	v_readlane_b32 s6, v253, 24
	v_lshl_add_u64 v[0:1], s[4:5], 0, v[92:93]
	v_lshlrev_b64 v[0:1], 10, v[0:1]
	v_or3_b32 v0, v128, s6, v0
	v_lshl_add_u64 v[2:3], v[0:1], 2, v[86:87]
	v_or_b32_e32 v6, 0x400, v0
	v_mov_b32_e32 v7, v1
	v_or_b32_e32 v14, 0x800, v0
	v_mov_b32_e32 v15, v1
	v_or_b32_e32 v18, 0xc00, v0
	v_mov_b32_e32 v19, v1
	v_lshl_add_u64 v[4:5], v[0:1], 1, v[88:89]
	v_lshl_add_u64 v[12:13], v[6:7], 2, v[86:87]
	v_lshl_add_u64 v[6:7], v[6:7], 1, v[88:89]
	v_lshl_add_u64 v[16:17], v[14:15], 2, v[86:87]
	v_lshl_add_u64 v[14:15], v[14:15], 1, v[88:89]
	v_lshl_add_u64 v[20:21], v[18:19], 2, v[86:87]
	v_lshl_add_u64 v[18:19], v[18:19], 1, v[88:89]
	global_load_dword v129, v[2:3], off
	global_load_ushort v130, v[4:5], off
	global_load_dword v131, v[12:13], off
	global_load_ushort v132, v[6:7], off
	global_load_dword v133, v[16:17], off
	global_load_ushort v134, v[14:15], off
	global_load_dword v135, v[20:21], off
	global_load_ushort v136, v[18:19], off
	v_or_b32_e32 v2, 0x1000, v0
	v_mov_b32_e32 v3, v1
	v_lshl_add_u64 v[4:5], v[2:3], 2, v[86:87]
	v_lshl_add_u64 v[2:3], v[2:3], 1, v[88:89]
	v_or_b32_e32 v6, 0x1400, v0
	v_mov_b32_e32 v7, v1
	v_or_b32_e32 v14, 0x1800, v0
	v_mov_b32_e32 v15, v1
	v_or_b32_e32 v18, 0x1c00, v0
	v_mov_b32_e32 v19, v1
	v_lshl_add_u64 v[12:13], v[6:7], 2, v[86:87]
	v_lshl_add_u64 v[6:7], v[6:7], 1, v[88:89]
	v_lshl_add_u64 v[16:17], v[14:15], 2, v[86:87]
	v_lshl_add_u64 v[14:15], v[14:15], 1, v[88:89]
	v_lshl_add_u64 v[20:21], v[18:19], 2, v[86:87]
	v_lshl_add_u64 v[18:19], v[18:19], 1, v[88:89]
	global_load_dword v137, v[4:5], off
	global_load_ushort v138, v[2:3], off
	global_load_dword v139, v[12:13], off
	global_load_ushort v140, v[6:7], off
	global_load_dword v142, v[16:17], off
	global_load_ushort v144, v[14:15], off
	global_load_dword v148, v[20:21], off
	global_load_ushort v150, v[18:19], off
	v_or_b32_e32 v2, 0x2000, v0
	v_mov_b32_e32 v3, v1
	v_lshl_add_u64 v[4:5], v[2:3], 2, v[86:87]
	v_lshl_add_u64 v[2:3], v[2:3], 1, v[88:89]
	v_or_b32_e32 v6, 0x2400, v0
	v_mov_b32_e32 v7, v1
	v_or_b32_e32 v14, 0x2800, v0
	v_mov_b32_e32 v15, v1
	v_or_b32_e32 v18, 0x2c00, v0
	v_mov_b32_e32 v19, v1
	v_lshl_add_u64 v[12:13], v[6:7], 2, v[86:87]
	v_lshl_add_u64 v[6:7], v[6:7], 1, v[88:89]
	v_lshl_add_u64 v[16:17], v[14:15], 2, v[86:87]
	v_lshl_add_u64 v[14:15], v[14:15], 1, v[88:89]
	v_lshl_add_u64 v[20:21], v[18:19], 2, v[86:87]
	v_lshl_add_u64 v[18:19], v[18:19], 1, v[88:89]
	global_load_dword v152, v[4:5], off
	global_load_ushort v153, v[2:3], off
	global_load_dword v154, v[12:13], off
	global_load_ushort v155, v[6:7], off
	global_load_dword v156, v[16:17], off
	global_load_ushort v170, v[14:15], off
	global_load_dword v173, v[20:21], off
	global_load_ushort v174, v[18:19], off
	v_or_b32_e32 v2, 0x3000, v0
	v_mov_b32_e32 v3, v1
	v_lshl_add_u64 v[4:5], v[2:3], 2, v[86:87]
	v_or_b32_e32 v6, 0x3400, v0
	v_mov_b32_e32 v7, v1
	v_or_b32_e32 v14, 0x3800, v0
	v_mov_b32_e32 v15, v1
	v_or_b32_e32 v0, 0x3c00, v0
	v_lshl_add_u64 v[2:3], v[2:3], 1, v[88:89]
	v_lshl_add_u64 v[12:13], v[6:7], 2, v[86:87]
	v_lshl_add_u64 v[6:7], v[6:7], 1, v[88:89]
	v_lshl_add_u64 v[16:17], v[14:15], 2, v[86:87]
	v_lshl_add_u64 v[14:15], v[14:15], 1, v[88:89]
	v_lshl_add_u64 v[18:19], v[0:1], 2, v[86:87]
	v_lshl_add_u64 v[0:1], v[0:1], 1, v[88:89]
	global_load_dword v175, v[4:5], off
	global_load_ushort v176, v[2:3], off
	global_load_dword v177, v[12:13], off
	global_load_ushort v178, v[6:7], off
	global_load_dword v179, v[16:17], off
	global_load_ushort v180, v[14:15], off
	global_load_dword v181, v[18:19], off
	global_load_ushort v182, v[0:1], off
	v_add_u32_e32 v4, 0x200, v8
	v_ashrrev_i32_e32 v94, 4, v8
	v_ashrrev_i32_e32 v96, 4, v4
	s_lshl_b32 s36, s6, 1
	v_lshlrev_b32_e32 v2, 4, v8
	v_ashrrev_i32_e32 v95, 31, v94
	v_ashrrev_i32_e32 v97, 31, v96
	v_lshl_add_u64 v[0:1], v[10:11], 0, s[36:37]
	v_and_b32_e32 v160, 0xf0, v2
	v_lshl_add_u64 v[2:3], s[4:5], 0, v[94:95]
	v_lshl_add_u64 v[4:5], s[4:5], 0, v[96:97]
	v_lshl_add_u64 v[0:1], v[0:1], 0, v[160:161]
	v_lshlrev_b64 v[2:3], 11, v[2:3]
	v_lshlrev_b64 v[4:5], 11, v[4:5]
; DI void hg_out_units(LAS unsigned char* L, int u0, int G, const float* LOGF, const bf16* QHG, const bf16* IHG, const bf16* GHG, const bf16* ST, const float* og, bf16* MIX, int tid, int wave, int lane) {
;     ...
;     const bf16* stp = ST + (size_t)unit * 16384;
;     bf16x8 stf[4][4]; u32x2 gtv[4];
; #pragma unroll
;     for (int d = 0; d < 4; ++d) { const int dt = 4 * dh + d;
; #pragma unroll
;         for (int ks = 0; ks < 4; ++ks) stf[d][ks] = *(const bf16x8*)(stp + (size_t)(16 * dt + lr) * 128 + 32 * ks + quad * 8);
	v_lshl_add_u64 v[2:3], v[0:1], 0, v[2:3]
	v_lshl_add_u64 v[4:5], v[0:1], 0, v[4:5]
	global_load_dwordx4 v[0:3], v[2:3], off
	s_nop 0
	global_load_dwordx4 v[4:7], v[4:5], off
	v_readlane_b32 s22, v252, 53
	s_ashr_i32 s1, s0, 6
	s_ashr_i32 s22, s0, 7
	v_readlane_b32 s23, v252, 54
	v_and_b32_e32 v22, 15, v8
	s_and_b32 s74, s1, 1
	s_lshl_b32 s98, s1, 10
	s_add_i32 s98, s98, 0x15000
	v_mov_b32_e32 v234, s98
	v_mov_b32_e32 v233, 0
	v_lshrrev_b32_e32 v230, 4, v8
	v_and_b32_e32 v231, 15, v230
	v_xor_b32_e32 v231, v22, v231
	v_lshlrev_b32_e32 v230, 8, v230
	v_lshl_add_u32 v230, v231, 4, v230
	v_and_b32_e32 v231, 48, v8
	v_sub_u32_e32 v224, v230, v231
	v_add_u32_e32 v224, 0x7000000, v224
	v_mov_b32_e32 v225, 0
	s_lshl_b32 s98, s74, 14
	s_add_i32 s98, s98, 0x15000
	v_lshl_add_u32 v230, v22, 8, s98
	v_bfe_u32 v231, v8, 4, 2
	v_xor_b32_e32 v232, v231, v22
	v_lshl_add_u32 v226, v232, 4, v230
	v_or_b32_e32 v232, 4, v231
	v_xor_b32_e32 v232, v232, v22
	v_lshl_add_u32 v227, v232, 4, v230
	v_or_b32_e32 v232, 8, v231
	v_xor_b32_e32 v232, v232, v22
	v_lshl_add_u32 v228, v232, 4, v230
	v_or_b32_e32 v232, 12, v231
	v_xor_b32_e32 v232, v232, v22
	v_lshl_add_u32 v229, v232, 4, v230
	s_lshl_b32 s4, s22, 4
	s_lshl_b32 s1, s1, 1
	v_or_b32_e32 v98, s4, v22
	s_and_b32 s23, s1, 2
	s_movk_i32 s1, 0x90
	s_and_b32 s0, s0, 0xffffff80
	s_lshl_b32 s6, s74, 2
	v_mul_lo_u32 v16, v98, s1
	v_readlane_b32 s1, v254, 60
	s_add_i32 s0, s0, 0
	s_add_i32 s0, s0, s6
	v_add_u32_e32 v145, s1, v16
	s_movk_i32 s1, 0x110
	v_and_b32_e32 v9, 63, v8
	v_mul_lo_u32 v17, v98, s1
	s_add_i32 s0, s0, 0x14800
	v_bfe_u32 v24, v8, 4, 2
	s_ashr_i32 s5, s4, 31
	s_add_i32 s4, 0, 0x14000
	v_and_b32_e32 v100, 48, v8
	v_add_u32_e32 v17, 0, v17
	s_lshl_b32 s1, s74, 7
	v_lshl_add_u32 v149, v9, 3, s0
	s_lshl_b32 s36, s74, 6
	s_movk_i32 s0, 0x140
	v_lshlrev_b32_e32 v13, 3, v8
	v_lshlrev_b32_e32 v14, 3, v24
	s_waitcnt vmcnt(34)
	v_lshl_add_u32 v141, v8, 2, s4
	v_add_u32_e32 v147, v17, v100
	v_bfe_u32 v8, v8, 2, 2
	s_add_i32 s1, s1, 0
	s_or_b32 s75, s36, 16
	s_or_b32 s81, s36, 32
	s_or_b32 s84, s36, 48
	v_mul_lo_u32 v17, v94, s0
	v_mul_lo_u32 v18, v96, s0
	s_movk_i32 s0, 0x880
	v_readlane_b32 s14, v252, 45
	v_add_u32_e32 v146, v145, v14
	v_or_b32_e32 v14, v14, v8
	v_and_b32_e32 v8, 24, v13
	v_lshl_add_u64 v[102:103], v[10:11], 0, v[160:161]
	v_mul_lo_u32 v10, v23, s0
	s_cmp_le_i32 s23, s22
	v_add_u32_e32 v13, s1, v8
	v_or_b32_e32 v10, v10, v128
	s_cselect_b64 s[0:1], -1, 0
	s_lshl_b32 s14, s23, 4
	v_lshlrev_b32_e32 v12, 2, v24
	v_lshl_add_u32 v151, v10, 1, 0
	v_or_b32_e32 v10, s14, v22
	s_lshl_b32 s93, s23, 5
	s_or_b32 s80, s23, 1
	v_readlane_b32 s15, v252, 46
	v_readlane_b32 s16, v252, 47
	v_readlane_b32 s17, v252, 48
	v_mul_u32_u24_e32 v19, 0x110, v10
	v_or_b32_e32 v10, s14, v12
	s_cmp_lt_i32 s23, s22
	v_readlane_b32 s20, v252, 51
	v_readlane_b32 s21, v252, 52
	v_cmp_gt_i32_e64 s[14:15], v10, v98
	v_cmp_lt_i32_e64 s[16:17], v10, v98
	v_or_b32_e32 v11, 2, v10
	v_or_b32_e32 v10, 3, v10
	s_cselect_b64 s[34:35], -1, 0
	s_lshl_b32 s22, s80, 4
	v_cmp_gt_i32_e64 s[20:21], v10, v98
	v_or_b32_e32 v10, s22, v22
	v_readlane_b32 s18, v252, 49
	v_readlane_b32 s19, v252, 50
	v_or_b32_e32 v8, s36, v12
	v_mul_u32_u24_e32 v20, 0x110, v10
	v_or_b32_e32 v10, s22, v12
	v_add_u32_e32 v15, 0, v160
	v_cmp_gt_i32_e64 s[18:19], v11, v98
	v_cmp_gt_i32_e64 s[22:23], v10, v98
	v_cmp_lt_i32_e64 s[62:63], v10, v98
	v_or_b32_e32 v11, 2, v10
	v_or_b32_e32 v10, 3, v10
	v_lshlrev_b32_e32 v160, 2, v8
	v_mov_b32_e32 v101, v161
	v_mov_b32_e32 v99, s5
	v_lshl_add_u32 v143, v128, 2, s4
	v_cmp_gt_u32_e64 s[4:5], 16, v9
	v_lshlrev_b32_e32 v9, 3, v98
	v_cmp_gt_i32_e64 s[26:27], v11, v98
	v_cmp_gt_i32_e64 s[28:29], v10, v98
	v_lshl_add_u64 v[104:105], s[68:69], 0, v[160:161]
	s_lshl_b32 s68, s74, 14
	v_lshl_add_u64 v[10:11], s[24:25], 0, v[100:101]
	v_readlane_b32 s24, v254, 30
	v_readlane_b32 s9, v252, 40
	v_readlane_b32 s12, v252, 43
	v_readlane_b32 s13, v252, 44
	v_add_u32_e32 v16, 0, v100
	v_mul_u32_u24_e32 v14, 0x140, v14
	v_lshl_or_b32 v21, v22, 8, s68
	v_readlane_b32 s25, v254, 31
	s_lshl_b32 s74, s84, 1
	v_add_u32_e32 v9, 0, v9
	v_readlane_b32 s84, v254, 36
	v_cmp_lt_i32_e64 s[6:7], 0, v23
	v_cmp_lt_i32_e64 s[8:9], 1, v23
	v_cmp_lt_i32_e64 s[10:11], 2, v23
	v_cmp_lt_i32_e64 s[12:13], 3, v23
	s_lshl_b32 s94, s80, 5
	v_or_b32_e32 v106, 0x7000080, v21
	v_mov_b32_e32 v107, v161
	v_lshl_add_u64 v[108:109], s[24:25], 0, v[10:11]
	v_or_b32_e32 v110, 0x7003080, v21
	v_mov_b32_e32 v111, v161
	v_or_b32_e32 v112, 0x7002080, v21
	v_mov_b32_e32 v113, v161
	v_or_b32_e32 v114, 0x7001080, v21
	v_mov_b32_e32 v115, v161
	v_lshlrev_b32_e32 v160, 1, v12
	s_lshl_b32 s80, s36, 1
	s_lshl_b32 s24, s75, 1
	s_lshl_b32 s68, s81, 1
	v_add_u32_e32 v101, v15, v17
	v_add_u32_e32 v157, v15, v18
	v_add_u32_e32 v158, v16, v19
	v_add_u32_e32 v159, v16, v20
	v_add_u32_e32 v171, v13, v14
	v_add_u32_e32 v172, 0x14800, v9
	v_lshlrev_b32_e32 v116, 1, v8
	v_readlane_b32 s95, v253, 23
	v_readlane_b32 s96, v253, 20
	s_mov_b32 s97, s84
	v_readlane_b32 s85, v254, 37
	global_load_dwordx4 v[208:211], v[104:105], off
	global_load_dwordx4 v[212:215], v[104:105], off offset:64
	global_load_dwordx4 v[216:219], v[104:105], off offset:128
	global_load_dwordx4 v[220:223], v[104:105], off offset:192
	s_branch .LBB0_335

; #define LAS __attribute__((address_space(3)))
; DI void hg_out_units(LAS unsigned char* L, int u0, int G, const float* LOGF, const bf16* QHG, const bf16* IHG, const bf16* GHG, const bf16* ST, const float* og, bf16* MIX, int tid, int wave, int lane) {
;     ...
;     for (;;) {
;     const int bh = unit >> 6, n = unit & 63, b_ = bh >> 3, h = bh & 7; const size_t tok0 = (size_t)b_ * SEQ + n * 64;
;     const bf16* stp = ST + (size_t)unit * 16384;
;     bf16x8 stf[4][4]; u32x2 gtv[4];
; #pragma unroll
;     for (int d = 0; d < 4; ++d) { const int dt = 4 * dh + d;
; #pragma unroll
;         for (int ks = 0; ks < 4; ++ks) stf[d][ks] = *(const bf16x8*)(stp + (size_t)(16 * dt + lr) * 128 + 32 * ks + quad * 8);
;         gtv[d] = *(const u32x2*)(GHG + (tok0 + 16 * tt + lr) * 1024 + h * 128 + 16 * dt + quad * 4); }
;     float tot = 0.f;
; #pragma unroll
;     for (int i = 0; i < 16; ++i) tot += g[i];
;     segtot[seg * 128 + c] = tot;
; #pragma unroll
;     for (int i = 0; i < 2; ++i) { const int cid = tid + 512 * i, kv = cid >> 4, dvs = (cid & 15) * 8; *(LAS bf16x8*)(Vs + kv * 160 + dvs) = v8[i]; }
;     __syncthreads();
.LBB0_335:
	s_ashr_i32 s86, s97, 9
	s_ashr_i32 s87, s86, 31
	s_lshl_b64 s[86:87], s[86:87], 12
	s_and_b32 s25, s96, 0xfc0
	s_or_b32 s86, s86, s25
	v_lshl_add_u64 v[126:127], s[86:87], 0, v[98:99]
	v_lshlrev_b64 v[8:9], 11, v[126:127]
	s_and_b32 s25, s95, 0x380
	v_lshl_add_u64 v[8:9], v[90:91], 0, v[8:9]
	s_lshl_b32 s36, s25, 1
	v_lshl_add_u64 v[8:9], v[8:9], 0, s[36:37]
	v_lshl_add_u64 v[72:73], v[8:9], 0, v[160:161]
	v_readfirstlane_b32 s99, v234
	v_lshl_add_u64 v[230:231], v[108:109], 0, v[224:225]
	s_mov_b32 m0, s99
	s_nop 0
	global_load_lds_dwordx4 v[230:231], off
	v_add_u32_e32 v232, 0x2000, v224
	v_lshl_add_u64 v[230:231], v[108:109], 0, v[232:233]
	s_add_i32 m0, s99, 0x2000
	s_nop 0
	global_load_lds_dwordx4 v[230:231], off
	v_add_u32_e32 v232, 0x4000, v224
	v_lshl_add_u64 v[230:231], v[108:109], 0, v[232:233]
	s_add_i32 m0, s99, 0x4000
	s_nop 0
	global_load_lds_dwordx4 v[230:231], off
	v_add_u32_e32 v232, 0x6000, v224
	v_lshl_add_u64 v[230:231], v[108:109], 0, v[232:233]
	s_add_i32 m0, s99, 0x6000
	s_nop 0
	global_load_lds_dwordx4 v[230:231], off
	s_mov_b32 s81, s37
	v_lshl_add_u64 v[8:9], v[72:73], 0, s[80:81]
	global_load_dwordx2 v[124:125], v[8:9], off
	s_mov_b32 s25, s37
	v_lshl_add_u64 v[8:9], v[72:73], 0, s[24:25]
	global_load_dwordx2 v[122:123], v[8:9], off
	s_mov_b32 s69, s37
	v_lshl_add_u64 v[8:9], v[72:73], 0, s[68:69]
	global_load_dwordx2 v[120:121], v[8:9], off
	s_mov_b32 s75, s37
	v_lshl_add_u64 v[72:73], v[72:73], 0, s[74:75]
	global_load_dwordx2 v[118:119], v[72:73], off
	s_waitcnt vmcnt(41)
	v_add_f32_e32 v72, 0, v129
	s_waitcnt vmcnt(39)
	v_add_f32_e32 v72, v72, v131
	s_waitcnt vmcnt(37)
	v_add_f32_e32 v72, v72, v133
	s_waitcnt vmcnt(35)
	v_add_f32_e32 v72, v72, v135
	s_waitcnt vmcnt(33)
	v_add_f32_e32 v72, v72, v137
	s_waitcnt vmcnt(31)
	v_add_f32_e32 v72, v72, v139
	s_waitcnt vmcnt(29)
	v_add_f32_e32 v72, v72, v142
	s_waitcnt vmcnt(27)
	v_add_f32_e32 v72, v72, v148
	s_waitcnt vmcnt(25)
	v_add_f32_e32 v72, v72, v152
	s_waitcnt vmcnt(23)
	v_add_f32_e32 v72, v72, v154
	s_waitcnt vmcnt(21)
	v_add_f32_e32 v72, v72, v156
	s_waitcnt vmcnt(19)
	v_add_f32_e32 v72, v72, v173
	s_waitcnt vmcnt(17)
	v_add_f32_e32 v72, v72, v175
	s_waitcnt vmcnt(15)
	v_add_f32_e32 v72, v72, v177
	s_waitcnt vmcnt(13)
	v_add_f32_e32 v72, v72, v179
	v_mov_b32_e32 v73, 0
	s_waitcnt vmcnt(11)
	v_add_f32_e32 v72, v72, v181
	ds_write_b32 v141, v72
	s_waitcnt vmcnt(9)
	ds_write_b128 v101, v[0:3] offset:52224
	s_waitcnt vmcnt(8)
	ds_write_b128 v157, v[4:7] offset:52224
	s_waitcnt lgkmcnt(0)
	s_barrier
	s_and_saveexec_b64 s[86:87], s[6:7]
	s_cbranch_execz .LBB0_337
	ds_read_b32 v72, v143
	s_waitcnt lgkmcnt(0)
	v_add_f32_e32 v73, 0, v72

;     DI void operator()(const pg8::f32x4 (&acc)[2][2][4][2], const pg8::Unit& u, int wr, int wc, int fr, int fq) const {
;         const int row0 = u.pm * 256 + wr * 64 + fr, col0 = u.pn * 256 + wc * 32 + 8 * fq;
; #pragma unroll
;         for (int ai = 0; ai < 2; ++ai)
; #pragma unroll
;             for (int m = 0; m < 4; ++m) { float* rowp = O + (size_t)(row0 + ai * 128 + m * 16) * ldc + col0;
; #pragma unroll
;                 for (int bj = 0; bj < 2; ++bj) { *(f32x4*)(rowp + bj * 128) = acc[ai][bj][m][0]; *(f32x4*)(rowp + bj * 128 + 4) = acc[ai][bj][m][1]; } }
;     }
.LBB0_422:
	v_mbcnt_lo_u32_b32 v186, -1, 0
	v_mbcnt_hi_u32_b32 v186, -1, v186
	v_and_b32_e32 v186, 32, v186
	v_cmp_ne_u32_e32 vcc, 0, v186
	v_mov_b32_e32 v189, 0
	v_mov_b32_e32 v188, 0x50
	v_mov_b32_e32 v190, 16
	v_mov_b32_e32 v191, 0xffffffc0
	v_cndmask_b32_e32 v186, v190, v191, vcc
	v_cndmask_b32_e64 v187, 0, -1, vcc
	v_cndmask_b32_e64 v188, v188, 0, vcc
	v_lshl_add_u32 v144, s10, 8, v140
	v_lshl_or_b32 v146, s80, 8, v142
	v_ashrrev_i32_e32 v145, 31, v144
	v_ashrrev_i32_e32 v147, 31, v146
	v_lshlrev_b64 v[148:149], 13, v[144:145]
	v_lshl_add_u64 v[148:149], v[134:135], 0, v[148:149]
	v_lshlrev_b64 v[146:147], 2, v[146:147]
	v_lshl_add_u64 v[148:149], v[148:149], 0, v[146:147]
	v_permlane32_swap_b32_e32 v120, v124
	v_permlane32_swap_b32_e32 v121, v125
	v_permlane32_swap_b32_e32 v122, v126
	v_permlane32_swap_b32_e32 v123, v127
	v_permlane32_swap_b32_e32 v100, v108
	v_permlane32_swap_b32_e32 v101, v109
	v_permlane32_swap_b32_e32 v102, v110
	v_permlane32_swap_b32_e32 v103, v111
	v_lshl_add_u64 v[190:191], v[148:149], 0, v[186:187]
	v_lshl_add_u64 v[192:193], v[148:149], 0, v[188:189]
	global_store_dwordx4 v[190:191], v[120:123], off
	global_store_dwordx4 v[192:193], v[124:127], off
	global_store_dwordx4 v[190:191], v[100:103], off offset:512
	global_store_dwordx4 v[192:193], v[108:111], off offset:512
	s_mov_b32 s97, 0x100000
	s_mov_b64 s[22:23], 0x100000
	v_or_b32_e32 v100, 16, v144
	v_ashrrev_i32_e32 v101, 31, v100
	v_lshlrev_b64 v[100:101], 13, v[100:101]
	v_lshl_add_u64 v[100:101], v[134:135], 0, v[100:101]
	v_lshl_add_u64 v[100:101], v[100:101], 0, v[146:147]
	v_permlane32_swap_b32_e32 v112, v116
	v_permlane32_swap_b32_e32 v113, v117
	v_permlane32_swap_b32_e32 v114, v118
	v_permlane32_swap_b32_e32 v115, v119
	v_permlane32_swap_b32_e32 v84, v92
	v_permlane32_swap_b32_e32 v85, v93
	v_permlane32_swap_b32_e32 v86, v94
	v_permlane32_swap_b32_e32 v87, v95
	v_lshl_add_u64 v[190:191], v[100:101], 0, v[186:187]
	v_lshl_add_u64 v[192:193], v[100:101], 0, v[188:189]
	global_store_dwordx4 v[190:191], v[112:115], off
	global_store_dwordx4 v[192:193], v[116:119], off
	global_store_dwordx4 v[190:191], v[84:87], off offset:512
	global_store_dwordx4 v[192:193], v[92:95], off offset:512
	s_mov_b32 s10, 0x120000
	s_nop 0
	v_or_b32_e32 v84, 32, v144
	v_ashrrev_i32_e32 v85, 31, v84
	v_lshlrev_b64 v[84:85], 13, v[84:85]
	v_lshl_add_u64 v[84:85], v[134:135], 0, v[84:85]
	v_lshl_add_u64 v[84:85], v[84:85], 0, v[146:147]
	v_permlane32_swap_b32_e32 v96, v104
	v_permlane32_swap_b32_e32 v97, v105
	v_permlane32_swap_b32_e32 v98, v106
	v_permlane32_swap_b32_e32 v99, v107
	v_permlane32_swap_b32_e32 v72, v76
	v_permlane32_swap_b32_e32 v73, v77
	v_permlane32_swap_b32_e32 v74, v78
	v_permlane32_swap_b32_e32 v75, v79
	v_lshl_add_u64 v[190:191], v[84:85], 0, v[186:187]
	v_lshl_add_u64 v[192:193], v[84:85], 0, v[188:189]
	global_store_dwordx4 v[190:191], v[96:99], off
	global_store_dwordx4 v[192:193], v[104:107], off
	global_store_dwordx4 v[190:191], v[72:75], off offset:512
	global_store_dwordx4 v[192:193], v[76:79], off offset:512
	s_nop 1
	v_or_b32_e32 v72, 48, v144
	v_ashrrev_i32_e32 v73, 31, v72
	v_lshlrev_b64 v[72:73], 13, v[72:73]
	v_lshl_add_u64 v[72:73], v[134:135], 0, v[72:73]
	v_lshl_add_u64 v[72:73], v[72:73], 0, v[146:147]
	v_permlane32_swap_b32_e32 v80, v88
	v_permlane32_swap_b32_e32 v81, v89
	v_permlane32_swap_b32_e32 v82, v90
	v_permlane32_swap_b32_e32 v83, v91
	v_permlane32_swap_b32_e32 v64, v68
	v_permlane32_swap_b32_e32 v65, v69
	v_permlane32_swap_b32_e32 v66, v70
	v_permlane32_swap_b32_e32 v67, v71
	v_lshl_add_u64 v[190:191], v[72:73], 0, v[186:187]
	v_lshl_add_u64 v[192:193], v[72:73], 0, v[188:189]
	global_store_dwordx4 v[190:191], v[80:83], off
	global_store_dwordx4 v[192:193], v[88:91], off
	global_store_dwordx4 v[190:191], v[64:67], off offset:512
	global_store_dwordx4 v[192:193], v[68:71], off offset:512
	s_nop 1
	v_add_co_u32_e32 v66, vcc, s97, v148
	v_lshl_add_u64 v[64:65], v[148:149], 0, s[22:23]
	s_nop 0
	v_addc_co_u32_e32 v67, vcc, 0, v149, vcc
	v_permlane32_swap_b32_e32 v56, v60
	v_permlane32_swap_b32_e32 v57, v61
	v_permlane32_swap_b32_e32 v58, v62
	v_permlane32_swap_b32_e32 v59, v63
	v_permlane32_swap_b32_e32 v40, v44
	v_permlane32_swap_b32_e32 v41, v45
	v_permlane32_swap_b32_e32 v42, v46
	v_permlane32_swap_b32_e32 v43, v47
	v_lshl_add_u64 v[190:191], v[64:65], 0, v[186:187]
	v_lshl_add_u64 v[192:193], v[64:65], 0, v[188:189]
	global_store_dwordx4 v[190:191], v[56:59], off
	global_store_dwordx4 v[192:193], v[60:63], off
	global_store_dwordx4 v[190:191], v[40:43], off offset:512
	global_store_dwordx4 v[192:193], v[44:47], off offset:512
	s_mov_b64 s[22:23], 0x120000
	s_nop 0
	v_add_co_u32_e32 v42, vcc, s10, v148
	s_mov_b32 s10, 0x140000
	s_nop 0
	v_addc_co_u32_e32 v43, vcc, 0, v149, vcc
	v_lshl_add_u64 v[40:41], v[148:149], 0, s[22:23]
	v_permlane32_swap_b32_e32 v48, v52
	v_permlane32_swap_b32_e32 v49, v53
	v_permlane32_swap_b32_e32 v50, v54
	v_permlane32_swap_b32_e32 v51, v55
	v_permlane32_swap_b32_e32 v24, v28
	v_permlane32_swap_b32_e32 v25, v29
	v_permlane32_swap_b32_e32 v26, v30
	v_permlane32_swap_b32_e32 v27, v31
	v_lshl_add_u64 v[190:191], v[40:41], 0, v[186:187]
	v_lshl_add_u64 v[192:193], v[40:41], 0, v[188:189]
	global_store_dwordx4 v[190:191], v[48:51], off
	global_store_dwordx4 v[192:193], v[52:55], off
	global_store_dwordx4 v[190:191], v[24:27], off offset:512
	global_store_dwordx4 v[192:193], v[28:31], off offset:512
	s_mov_b64 s[22:23], 0x140000
	s_nop 0
	v_add_co_u32_e32 v26, vcc, s10, v148
	v_lshl_add_u64 v[24:25], v[148:149], 0, s[22:23]
	s_nop 0
	v_addc_co_u32_e32 v27, vcc, 0, v149, vcc
	v_permlane32_swap_b32_e32 v32, v36
	v_permlane32_swap_b32_e32 v33, v37
	v_permlane32_swap_b32_e32 v34, v38
	v_permlane32_swap_b32_e32 v35, v39
	v_permlane32_swap_b32_e32 v8, v12
	v_permlane32_swap_b32_e32 v9, v13
	v_permlane32_swap_b32_e32 v10, v14
	v_permlane32_swap_b32_e32 v11, v15
	v_lshl_add_u64 v[190:191], v[24:25], 0, v[186:187]
	v_lshl_add_u64 v[192:193], v[24:25], 0, v[188:189]
	global_store_dwordx4 v[190:191], v[32:35], off
	global_store_dwordx4 v[192:193], v[36:39], off
	global_store_dwordx4 v[190:191], v[8:11], off offset:512
	global_store_dwordx4 v[192:193], v[12:15], off offset:512
	s_nop 1
	v_add_co_u32_e32 v10, vcc, 0x160000, v148
	v_lshl_add_u64 v[8:9], v[148:149], 0, s[90:91]
	s_nop 0
	v_addc_co_u32_e32 v11, vcc, 0, v149, vcc
	s_andn2_b64 vcc, exec, s[8:9]
	s_mov_b64 s[8:9], -1
	v_permlane32_swap_b32_e32 v16, v20
	v_permlane32_swap_b32_e32 v17, v21
	v_permlane32_swap_b32_e32 v18, v22
	v_permlane32_swap_b32_e32 v19, v23
	v_permlane32_swap_b32_e32 v0, v4
	v_permlane32_swap_b32_e32 v1, v5
	v_permlane32_swap_b32_e32 v2, v6
	v_permlane32_swap_b32_e32 v3, v7
	v_lshl_add_u64 v[190:191], v[8:9], 0, v[186:187]
	v_lshl_add_u64 v[192:193], v[8:9], 0, v[188:189]
	global_store_dwordx4 v[190:191], v[16:19], off
	global_store_dwordx4 v[192:193], v[20:23], off
	global_store_dwordx4 v[190:191], v[0:3], off offset:512
	global_store_dwordx4 v[192:193], v[4:7], off offset:512
	s_cbranch_vccnz .LBB0_411
; #define PG8_BAR __builtin_amdgcn_s_barrier()
; template <class Epi, class Sched, bool ALIGN_EPI = false, bool SP2 = false>
; __device__ __forceinline__ void gemm_phase(PG8_LAS unsigned char* lds, const Gemm g, const Sched& S, const Epi& E, int tid_in) {
;     ...
;         if constexpr (ALIGN_EPI) { if (wr == 0) PG8_BAR; }
;         if constexpr (!Epi::AFTER_DRAIN) { E(acc, cur, wr, wc, fr, fq); S.done(cur); }
;         if (!has_next) break;
; #pragma unroll
;         for (int a = 0; a < 2; ++a)
; #pragma unroll
;             for (int b = 0; b < 2; ++b)
; #pragma unroll
;                 for (int m = 0; m < 4; ++m)
; #pragma unroll
;                     for (int n = 0; n < 2; ++n) acc[a][b][m][n] = (f32x4){0.f, 0.f, 0.f, 0.f};
;         cur = nxt; cA = nA; cB = nB; ++ui;
;         if constexpr (ALIGN_EPI) { if (wr == 1) PG8_BAR; }
;     }
	s_andn2_b64 vcc, exec, s[0:1]
	s_cbranch_vccnz .LBB0_410
	s_barrier
	s_branch .LBB0_410

;     DI void operator()(const pg8::f32x4 (&acc)[2][2][4][2], const pg8::Unit& u, int wr, int wc, int fr, int fq) const {
;         const int row0 = u.pm * 256 + wr * 64 + fr, col0 = u.pn * 256 + wc * 32 + 8 * fq;
; #pragma unroll
;         for (int ai = 0; ai < 2; ++ai)
; #pragma unroll
;             for (int m = 0; m < 4; ++m) { float* rowp = O + (size_t)(row0 + ai * 128 + m * 16) * ldc + col0;
; #pragma unroll
;                 for (int bj = 0; bj < 2; ++bj) { *(f32x4*)(rowp + bj * 128) = acc[ai][bj][m][0]; *(f32x4*)(rowp + bj * 128 + 4) = acc[ai][bj][m][1]; } }
;     }
.LBB0_738:
	v_mbcnt_lo_u32_b32 v186, -1, 0
	v_mbcnt_hi_u32_b32 v186, -1, v186
	v_and_b32_e32 v186, 32, v186
	v_cmp_ne_u32_e32 vcc, 0, v186
	v_mov_b32_e32 v189, 0
	v_mov_b32_e32 v188, 0x50
	v_mov_b32_e32 v190, 16
	v_mov_b32_e32 v191, 0xffffffc0
	v_cndmask_b32_e32 v186, v190, v191, vcc
	v_cndmask_b32_e64 v187, 0, -1, vcc
	v_cndmask_b32_e64 v188, v188, 0, vcc
	v_lshl_add_u32 v144, s12, 8, v140
	v_lshl_or_b32 v146, s84, 8, v142
	v_ashrrev_i32_e32 v145, 31, v144
	v_ashrrev_i32_e32 v147, 31, v146
	v_lshlrev_b64 v[148:149], 13, v[144:145]
	v_lshl_add_u64 v[148:149], v[134:135], 0, v[148:149]
	v_lshlrev_b64 v[146:147], 2, v[146:147]
	v_lshl_add_u64 v[148:149], v[148:149], 0, v[146:147]
	v_permlane32_swap_b32_e32 v120, v124
	v_permlane32_swap_b32_e32 v121, v125
	v_permlane32_swap_b32_e32 v122, v126
	v_permlane32_swap_b32_e32 v123, v127
	v_permlane32_swap_b32_e32 v100, v108
	v_permlane32_swap_b32_e32 v101, v109
	v_permlane32_swap_b32_e32 v102, v110
	v_permlane32_swap_b32_e32 v103, v111
	v_lshl_add_u64 v[190:191], v[148:149], 0, v[186:187]
	v_lshl_add_u64 v[192:193], v[148:149], 0, v[188:189]
	global_store_dwordx4 v[190:191], v[120:123], off
	global_store_dwordx4 v[192:193], v[124:127], off
	global_store_dwordx4 v[190:191], v[100:103], off offset:512
	global_store_dwordx4 v[192:193], v[108:111], off offset:512
	s_mov_b64 s[24:25], 0x100000
	s_mov_b32 s12, 0x120000
	v_or_b32_e32 v100, 16, v144
	v_ashrrev_i32_e32 v101, 31, v100
	v_lshlrev_b64 v[100:101], 13, v[100:101]
	v_lshl_add_u64 v[100:101], v[134:135], 0, v[100:101]
	v_lshl_add_u64 v[100:101], v[100:101], 0, v[146:147]
	v_permlane32_swap_b32_e32 v112, v116
	v_permlane32_swap_b32_e32 v113, v117
	v_permlane32_swap_b32_e32 v114, v118
	v_permlane32_swap_b32_e32 v115, v119
	v_permlane32_swap_b32_e32 v84, v92
	v_permlane32_swap_b32_e32 v85, v93
	v_permlane32_swap_b32_e32 v86, v94
	v_permlane32_swap_b32_e32 v87, v95
	v_lshl_add_u64 v[190:191], v[100:101], 0, v[186:187]
	v_lshl_add_u64 v[192:193], v[100:101], 0, v[188:189]
	global_store_dwordx4 v[190:191], v[112:115], off
	global_store_dwordx4 v[192:193], v[116:119], off
	global_store_dwordx4 v[190:191], v[84:87], off offset:512
	global_store_dwordx4 v[192:193], v[92:95], off offset:512
	s_nop 1
	v_or_b32_e32 v84, 32, v144
	v_ashrrev_i32_e32 v85, 31, v84
	v_lshlrev_b64 v[84:85], 13, v[84:85]
	v_lshl_add_u64 v[84:85], v[134:135], 0, v[84:85]
	v_lshl_add_u64 v[84:85], v[84:85], 0, v[146:147]
	v_permlane32_swap_b32_e32 v96, v104
	v_permlane32_swap_b32_e32 v97, v105
	v_permlane32_swap_b32_e32 v98, v106
	v_permlane32_swap_b32_e32 v99, v107
	v_permlane32_swap_b32_e32 v72, v76
	v_permlane32_swap_b32_e32 v73, v77
	v_permlane32_swap_b32_e32 v74, v78
	v_permlane32_swap_b32_e32 v75, v79
	v_lshl_add_u64 v[190:191], v[84:85], 0, v[186:187]
	v_lshl_add_u64 v[192:193], v[84:85], 0, v[188:189]
	global_store_dwordx4 v[190:191], v[96:99], off
	global_store_dwordx4 v[192:193], v[104:107], off
	global_store_dwordx4 v[190:191], v[72:75], off offset:512
	global_store_dwordx4 v[192:193], v[76:79], off offset:512
	s_nop 1
	v_or_b32_e32 v72, 48, v144
	v_ashrrev_i32_e32 v73, 31, v72
	v_lshlrev_b64 v[72:73], 13, v[72:73]
	v_lshl_add_u64 v[72:73], v[134:135], 0, v[72:73]
	v_lshl_add_u64 v[72:73], v[72:73], 0, v[146:147]
	v_permlane32_swap_b32_e32 v80, v88
	v_permlane32_swap_b32_e32 v81, v89
	v_permlane32_swap_b32_e32 v82, v90
	v_permlane32_swap_b32_e32 v83, v91
	v_permlane32_swap_b32_e32 v64, v68
	v_permlane32_swap_b32_e32 v65, v69
	v_permlane32_swap_b32_e32 v66, v70
	v_permlane32_swap_b32_e32 v67, v71
	v_lshl_add_u64 v[190:191], v[72:73], 0, v[186:187]
	v_lshl_add_u64 v[192:193], v[72:73], 0, v[188:189]
	global_store_dwordx4 v[190:191], v[80:83], off
	global_store_dwordx4 v[192:193], v[88:91], off
	global_store_dwordx4 v[190:191], v[64:67], off offset:512
	global_store_dwordx4 v[192:193], v[68:71], off offset:512
	s_nop 1
	v_add_co_u32_e32 v66, vcc, s97, v148
	v_lshl_add_u64 v[64:65], v[148:149], 0, s[24:25]
	s_nop 0
	v_addc_co_u32_e32 v67, vcc, 0, v149, vcc
	v_permlane32_swap_b32_e32 v56, v60
	v_permlane32_swap_b32_e32 v57, v61
	v_permlane32_swap_b32_e32 v58, v62
	v_permlane32_swap_b32_e32 v59, v63
	v_permlane32_swap_b32_e32 v40, v44
	v_permlane32_swap_b32_e32 v41, v45
	v_permlane32_swap_b32_e32 v42, v46
	v_permlane32_swap_b32_e32 v43, v47
	v_lshl_add_u64 v[190:191], v[64:65], 0, v[186:187]
	v_lshl_add_u64 v[192:193], v[64:65], 0, v[188:189]
	global_store_dwordx4 v[190:191], v[56:59], off
	global_store_dwordx4 v[192:193], v[60:63], off
	global_store_dwordx4 v[190:191], v[40:43], off offset:512
	global_store_dwordx4 v[192:193], v[44:47], off offset:512
	s_mov_b64 s[24:25], 0x120000
	s_nop 0
	v_add_co_u32_e32 v42, vcc, s12, v148
	s_mov_b32 s12, 0x140000
	s_nop 0
	v_addc_co_u32_e32 v43, vcc, 0, v149, vcc
	v_lshl_add_u64 v[40:41], v[148:149], 0, s[24:25]
	v_permlane32_swap_b32_e32 v48, v52
	v_permlane32_swap_b32_e32 v49, v53
	v_permlane32_swap_b32_e32 v50, v54
	v_permlane32_swap_b32_e32 v51, v55
	v_permlane32_swap_b32_e32 v24, v28
	v_permlane32_swap_b32_e32 v25, v29
	v_permlane32_swap_b32_e32 v26, v30
	v_permlane32_swap_b32_e32 v27, v31
	v_lshl_add_u64 v[190:191], v[40:41], 0, v[186:187]
	v_lshl_add_u64 v[192:193], v[40:41], 0, v[188:189]
	global_store_dwordx4 v[190:191], v[48:51], off
	global_store_dwordx4 v[192:193], v[52:55], off
	global_store_dwordx4 v[190:191], v[24:27], off offset:512
	global_store_dwordx4 v[192:193], v[28:31], off offset:512
	s_mov_b64 s[24:25], 0x140000
	s_nop 0
	v_add_co_u32_e32 v26, vcc, s12, v148
	v_lshl_add_u64 v[24:25], v[148:149], 0, s[24:25]
	s_nop 0
	v_addc_co_u32_e32 v27, vcc, 0, v149, vcc
	v_permlane32_swap_b32_e32 v32, v36
	v_permlane32_swap_b32_e32 v33, v37
	v_permlane32_swap_b32_e32 v34, v38
	v_permlane32_swap_b32_e32 v35, v39
	v_permlane32_swap_b32_e32 v8, v12
	v_permlane32_swap_b32_e32 v9, v13
	v_permlane32_swap_b32_e32 v10, v14
	v_permlane32_swap_b32_e32 v11, v15
	v_lshl_add_u64 v[190:191], v[24:25], 0, v[186:187]
	v_lshl_add_u64 v[192:193], v[24:25], 0, v[188:189]
	global_store_dwordx4 v[190:191], v[32:35], off
	global_store_dwordx4 v[192:193], v[36:39], off
	global_store_dwordx4 v[190:191], v[8:11], off offset:512
	global_store_dwordx4 v[192:193], v[12:15], off offset:512
	s_nop 1
	v_add_co_u32_e32 v10, vcc, 0x160000, v148
	v_lshl_add_u64 v[8:9], v[148:149], 0, s[90:91]
	s_nop 0
	v_addc_co_u32_e32 v11, vcc, 0, v149, vcc
	s_andn2_b64 vcc, exec, s[0:1]
	s_mov_b64 s[0:1], -1
	v_permlane32_swap_b32_e32 v16, v20
	v_permlane32_swap_b32_e32 v17, v21
	v_permlane32_swap_b32_e32 v18, v22
	v_permlane32_swap_b32_e32 v19, v23
	v_permlane32_swap_b32_e32 v0, v4
	v_permlane32_swap_b32_e32 v1, v5
	v_permlane32_swap_b32_e32 v2, v6
	v_permlane32_swap_b32_e32 v3, v7
	v_lshl_add_u64 v[190:191], v[8:9], 0, v[186:187]
	v_lshl_add_u64 v[192:193], v[8:9], 0, v[188:189]
	global_store_dwordx4 v[190:191], v[16:19], off
	global_store_dwordx4 v[192:193], v[20:23], off
	global_store_dwordx4 v[190:191], v[0:3], off offset:512
	global_store_dwordx4 v[192:193], v[4:7], off offset:512
	s_cbranch_vccnz .LBB0_727
; #define PG8_BAR __builtin_amdgcn_s_barrier()
; template <class Epi, class Sched, bool ALIGN_EPI = false, bool SP2 = false>
; __device__ __forceinline__ void gemm_phase(PG8_LAS unsigned char* lds, const Gemm g, const Sched& S, const Epi& E, int tid_in) {
;     ...
;         if constexpr (ALIGN_EPI) { if (wr == 0) PG8_BAR; }
;         if constexpr (!Epi::AFTER_DRAIN) { E(acc, cur, wr, wc, fr, fq); S.done(cur); }
;         if (!has_next) break;
; #pragma unroll
;         for (int a = 0; a < 2; ++a)
; #pragma unroll
;             for (int b = 0; b < 2; ++b)
; #pragma unroll
;                 for (int m = 0; m < 4; ++m)
; #pragma unroll
;                     for (int n = 0; n < 2; ++n) acc[a][b][m][n] = (f32x4){0.f, 0.f, 0.f, 0.f};
;         cur = nxt; cA = nA; cB = nB; ++ui;
;         if constexpr (ALIGN_EPI) { if (wr == 1) PG8_BAR; }
;     }
	s_andn2_b64 vcc, exec, s[8:9]
	s_cbranch_vccnz .LBB0_726
	s_barrier
	s_branch .LBB0_726

;     DI void operator()(const pg8::f32x4 (&acc)[2][2][4][2], const pg8::Unit& u, int wr, int wc, int fr, int fq) const {
;         const int row0 = u.pm * 256 + wr * 64 + fr, col0 = u.pn * 256 + wc * 32 + 8 * fq;
; #pragma unroll
;         for (int ai = 0; ai < 2; ++ai)
; #pragma unroll
;             for (int m = 0; m < 4; ++m) { float* rowp = O + (size_t)(row0 + ai * 128 + m * 16) * ldc + col0;
; #pragma unroll
;                 for (int bj = 0; bj < 2; ++bj) { *(f32x4*)(rowp + bj * 128) = acc[ai][bj][m][0]; *(f32x4*)(rowp + bj * 128 + 4) = acc[ai][bj][m][1]; } }
;     }
.LBB0_943:
	v_mbcnt_lo_u32_b32 v186, -1, 0
	v_mbcnt_hi_u32_b32 v186, -1, v186
	v_and_b32_e32 v186, 32, v186
	v_cmp_ne_u32_e32 vcc, 0, v186
	v_mov_b32_e32 v189, 0
	v_mov_b32_e32 v188, 0x50
	v_mov_b32_e32 v190, 16
	v_mov_b32_e32 v191, 0xffffffc0
	v_cndmask_b32_e32 v186, v190, v191, vcc
	v_cndmask_b32_e64 v187, 0, -1, vcc
	v_cndmask_b32_e64 v188, v188, 0, vcc
	v_lshl_add_u32 v148, s19, 8, v154
	v_lshl_or_b32 v150, s21, 8, v156
	v_ashrrev_i32_e32 v149, 31, v148
	v_ashrrev_i32_e32 v151, 31, v150
	v_lshlrev_b64 v[152:153], 13, v[148:149]
	v_lshl_add_u64 v[152:153], v[138:139], 0, v[152:153]
	v_lshlrev_b64 v[150:151], 2, v[150:151]
	v_lshl_add_u64 v[152:153], v[152:153], 0, v[150:151]
	v_permlane32_swap_b32_e32 v120, v124
	v_permlane32_swap_b32_e32 v121, v125
	v_permlane32_swap_b32_e32 v122, v126
	v_permlane32_swap_b32_e32 v123, v127
	v_permlane32_swap_b32_e32 v100, v108
	v_permlane32_swap_b32_e32 v101, v109
	v_permlane32_swap_b32_e32 v102, v110
	v_permlane32_swap_b32_e32 v103, v111
	v_lshl_add_u64 v[190:191], v[152:153], 0, v[186:187]
	v_lshl_add_u64 v[192:193], v[152:153], 0, v[188:189]
	global_store_dwordx4 v[190:191], v[120:123], off
	global_store_dwordx4 v[192:193], v[124:127], off
	global_store_dwordx4 v[190:191], v[100:103], off offset:512
	global_store_dwordx4 v[192:193], v[108:111], off offset:512
	s_mov_b64 s[4:5], 0x100000
	s_nop 0
	v_or_b32_e32 v100, 16, v148
	v_ashrrev_i32_e32 v101, 31, v100
	v_lshlrev_b64 v[100:101], 13, v[100:101]
	v_lshl_add_u64 v[100:101], v[138:139], 0, v[100:101]
	v_lshl_add_u64 v[100:101], v[100:101], 0, v[150:151]
	v_permlane32_swap_b32_e32 v112, v116
	v_permlane32_swap_b32_e32 v113, v117
	v_permlane32_swap_b32_e32 v114, v118
	v_permlane32_swap_b32_e32 v115, v119
	v_permlane32_swap_b32_e32 v84, v92
	v_permlane32_swap_b32_e32 v85, v93
	v_permlane32_swap_b32_e32 v86, v94
	v_permlane32_swap_b32_e32 v87, v95
	v_lshl_add_u64 v[190:191], v[100:101], 0, v[186:187]
	v_lshl_add_u64 v[192:193], v[100:101], 0, v[188:189]
	global_store_dwordx4 v[190:191], v[112:115], off
	global_store_dwordx4 v[192:193], v[116:119], off
	global_store_dwordx4 v[190:191], v[84:87], off offset:512
	global_store_dwordx4 v[192:193], v[92:95], off offset:512
	s_nop 1
	v_or_b32_e32 v84, 32, v148
	v_ashrrev_i32_e32 v85, 31, v84
	v_lshlrev_b64 v[84:85], 13, v[84:85]
	v_lshl_add_u64 v[84:85], v[138:139], 0, v[84:85]
	v_lshl_add_u64 v[84:85], v[84:85], 0, v[150:151]
	v_permlane32_swap_b32_e32 v96, v104
	v_permlane32_swap_b32_e32 v97, v105
	v_permlane32_swap_b32_e32 v98, v106
	v_permlane32_swap_b32_e32 v99, v107
	v_permlane32_swap_b32_e32 v72, v76
	v_permlane32_swap_b32_e32 v73, v77
	v_permlane32_swap_b32_e32 v74, v78
	v_permlane32_swap_b32_e32 v75, v79
	v_lshl_add_u64 v[190:191], v[84:85], 0, v[186:187]
	v_lshl_add_u64 v[192:193], v[84:85], 0, v[188:189]
	global_store_dwordx4 v[190:191], v[96:99], off
	global_store_dwordx4 v[192:193], v[104:107], off
	global_store_dwordx4 v[190:191], v[72:75], off offset:512
	global_store_dwordx4 v[192:193], v[76:79], off offset:512
	s_nop 1
	v_or_b32_e32 v72, 48, v148
	v_ashrrev_i32_e32 v73, 31, v72
	v_lshlrev_b64 v[72:73], 13, v[72:73]
	v_lshl_add_u64 v[72:73], v[138:139], 0, v[72:73]
	v_lshl_add_u64 v[72:73], v[72:73], 0, v[150:151]
	v_permlane32_swap_b32_e32 v80, v88
	v_permlane32_swap_b32_e32 v81, v89
	v_permlane32_swap_b32_e32 v82, v90
	v_permlane32_swap_b32_e32 v83, v91
	v_permlane32_swap_b32_e32 v64, v68
	v_permlane32_swap_b32_e32 v65, v69
	v_permlane32_swap_b32_e32 v66, v70
	v_permlane32_swap_b32_e32 v67, v71
	v_lshl_add_u64 v[190:191], v[72:73], 0, v[186:187]
	v_lshl_add_u64 v[192:193], v[72:73], 0, v[188:189]
	global_store_dwordx4 v[190:191], v[80:83], off
	global_store_dwordx4 v[192:193], v[88:91], off
	global_store_dwordx4 v[190:191], v[64:67], off offset:512
	global_store_dwordx4 v[192:193], v[68:71], off offset:512
	s_nop 1
	v_add_co_u32_e32 v66, vcc, s97, v152
	v_lshl_add_u64 v[64:65], v[152:153], 0, s[4:5]
	s_nop 0
	v_addc_co_u32_e32 v67, vcc, 0, v153, vcc
	s_mov_b64 s[4:5], 0x120000
	v_permlane32_swap_b32_e32 v56, v60
	v_permlane32_swap_b32_e32 v57, v61
	v_permlane32_swap_b32_e32 v58, v62
	v_permlane32_swap_b32_e32 v59, v63
	v_permlane32_swap_b32_e32 v40, v44
	v_permlane32_swap_b32_e32 v41, v45
	v_permlane32_swap_b32_e32 v42, v46
	v_permlane32_swap_b32_e32 v43, v47
	v_lshl_add_u64 v[190:191], v[64:65], 0, v[186:187]
	v_lshl_add_u64 v[192:193], v[64:65], 0, v[188:189]
	global_store_dwordx4 v[190:191], v[56:59], off
	global_store_dwordx4 v[192:193], v[60:63], off
	global_store_dwordx4 v[190:191], v[40:43], off offset:512
	global_store_dwordx4 v[192:193], v[44:47], off offset:512
	s_nop 1
	v_lshl_add_u64 v[40:41], v[152:153], 0, s[4:5]
	s_mov_b32 s4, 0x120000
	v_add_co_u32_e32 v42, vcc, s4, v152
	s_mov_b64 s[4:5], 0x140000
	s_nop 0
	v_addc_co_u32_e32 v43, vcc, 0, v153, vcc
	v_permlane32_swap_b32_e32 v48, v52
	v_permlane32_swap_b32_e32 v49, v53
	v_permlane32_swap_b32_e32 v50, v54
	v_permlane32_swap_b32_e32 v51, v55
	v_permlane32_swap_b32_e32 v24, v28
	v_permlane32_swap_b32_e32 v25, v29
	v_permlane32_swap_b32_e32 v26, v30
	v_permlane32_swap_b32_e32 v27, v31
	v_lshl_add_u64 v[190:191], v[40:41], 0, v[186:187]
	v_lshl_add_u64 v[192:193], v[40:41], 0, v[188:189]
	global_store_dwordx4 v[190:191], v[48:51], off
	global_store_dwordx4 v[192:193], v[52:55], off
	global_store_dwordx4 v[190:191], v[24:27], off offset:512
	global_store_dwordx4 v[192:193], v[28:31], off offset:512
	s_nop 1
	v_lshl_add_u64 v[24:25], v[152:153], 0, s[4:5]
	s_mov_b32 s4, 0x140000
	v_add_co_u32_e32 v26, vcc, s4, v152
	s_nop 1
	v_addc_co_u32_e32 v27, vcc, 0, v153, vcc
	v_permlane32_swap_b32_e32 v32, v36
	v_permlane32_swap_b32_e32 v33, v37
	v_permlane32_swap_b32_e32 v34, v38
	v_permlane32_swap_b32_e32 v35, v39
	v_permlane32_swap_b32_e32 v8, v12
	v_permlane32_swap_b32_e32 v9, v13
	v_permlane32_swap_b32_e32 v10, v14
	v_permlane32_swap_b32_e32 v11, v15
	v_lshl_add_u64 v[190:191], v[24:25], 0, v[186:187]
	v_lshl_add_u64 v[192:193], v[24:25], 0, v[188:189]
	global_store_dwordx4 v[190:191], v[32:35], off
	global_store_dwordx4 v[192:193], v[36:39], off
	global_store_dwordx4 v[190:191], v[8:11], off offset:512
	global_store_dwordx4 v[192:193], v[12:15], off offset:512
	s_nop 1
	v_add_co_u32_e32 v10, vcc, 0x160000, v152
	v_lshl_add_u64 v[8:9], v[152:153], 0, s[90:91]
	s_nop 0
	v_addc_co_u32_e32 v11, vcc, 0, v153, vcc
	s_and_b64 vcc, exec, s[0:1]
	s_mov_b64 s[0:1], -1
	v_permlane32_swap_b32_e32 v16, v20
	v_permlane32_swap_b32_e32 v17, v21
	v_permlane32_swap_b32_e32 v18, v22
	v_permlane32_swap_b32_e32 v19, v23
	v_permlane32_swap_b32_e32 v0, v4
	v_permlane32_swap_b32_e32 v1, v5
	v_permlane32_swap_b32_e32 v2, v6
	v_permlane32_swap_b32_e32 v3, v7
	v_lshl_add_u64 v[190:191], v[8:9], 0, v[186:187]
	v_lshl_add_u64 v[192:193], v[8:9], 0, v[188:189]
	global_store_dwordx4 v[190:191], v[16:19], off
	global_store_dwordx4 v[192:193], v[20:23], off
	global_store_dwordx4 v[190:191], v[0:3], off offset:512
	global_store_dwordx4 v[192:193], v[4:7], off offset:512
	s_cbranch_vccnz .LBB0_928
; #define PG8_BAR __builtin_amdgcn_s_barrier()
; template <class Epi, class Sched, bool ALIGN_EPI = false, bool SP2 = false>
; __device__ __forceinline__ void gemm_phase(PG8_LAS unsigned char* lds, const Gemm g, const Sched& S, const Epi& E, int tid_in) {
;     ...
;         cur = nxt; cA = nA; cB = nB; ++ui;
;         if constexpr (ALIGN_EPI) { if (wr == 1) PG8_BAR; }
;     }
	s_andn2_b64 vcc, exec, s[6:7]
	s_cbranch_vccnz .LBB0_927
	s_barrier
	s_branch .LBB0_927
